# A2 + indexer relu folded to one v_max per element (MFMA distances re-padded)
# baseline (speedup 1.0000x reference)
; #define LAS __attribute__((address_space(3)))
; #define IDX_WRITEK(buf) do { LAS unsigned char* d = lds + (buf) * (TK * PITCH) + srow * PITCH + sseg * 64; *(LAS u32x4*)d = st0; *(LAS u32x4*)(d + 16) = st1; *(LAS u32x4*)(d + 32) = st2; *(LAS u32x4*)(d + 48) = st3; } while (0)
; __device__ __forceinline__ void idx_stream(unsigned char* ws, LAS unsigned char* lds, int bb, int bid, int G, int wave, int lane, int tid) {
;     ...
;         for (int ct = 0; ct < TK / 32; ++ct) {
;             bf16x8 bfr[8];
; #pragma unroll
;             for (int ks = 0; ks < 8; ++ks) bfr[ks] = *(const LAS bf16x8*)(kb + ct * 32 * PITCH + ks * 32);
;             f32x16 c0, c1;
; #pragma unroll
;             for (int r = 0; r < 16; ++r) { c0[r] = 0.f; c1[r] = 0.f; }
; #pragma unroll
;             for (int ks = 0; ks < 8; ++ks) { c0 = __builtin_amdgcn_mfma_f32_32x32x16_bf16(af[0][ks], bfr[ks], c0, 0, 0, 0); c1 = __builtin_amdgcn_mfma_f32_32x32x16_bf16(af[1][ks], bfr[ks], c1, 0, 0, 0); }
;             float s0 = 0.f, s1 = 0.f;
; #pragma unroll
;             for (int r = 0; r < 16; ++r) { s0 += w[0][r] * fmaxf(c0[r], 0.f); s1 += w[1][r] * fmaxf(c1[r], 0.f); }
;             const int key = kt * TK + ct * 32 + rho, q = 32 * u + 4 * wave + hi;
;             SC[(size_t)q * SEQ + key] = (_Float16)s0; SC[(size_t)(q + 2) * SEQ + key] = (_Float16)s1;
;         }
;         if (g + 1 < g1) IDX_WRITEK(buf ^ 1);
.LBB0_1149:
	s_and_b32 s23, s7, 1
	s_mul_i32 s24, s23, 0x8800
	v_add_u32_e32 v191, s24, v187
	ds_read_b128 v[0:3], v191
	ds_read_b128 v[4:7], v191 offset:32
	v_lshl_add_u32 v20, s0, 5, v188
	v_ashrrev_i32_e32 v21, 31, v20
	v_lshlrev_b64 v[20:21], 14, v[20:21]
	s_waitcnt vmcnt(23) lgkmcnt(1)
	v_mfma_f32_32x32x16_bf16 v[48:63], v[64:67], v[0:3], 0
	v_lshl_add_u64 v[194:195], s[12:13], 0, v[20:21]
	s_lshl_b32 s24, s3, 7
	v_subrev_u32_e32 v192, s24, v190
	s_waitcnt vmcnt(11)
	v_mfma_f32_32x32x16_bf16 v[32:47], v[112:115], v[0:3], 0
	s_waitcnt lgkmcnt(0)
	v_mfma_f32_32x32x16_bf16 v[48:63], v[68:71], v[4:7], v[48:63]
	s_waitcnt vmcnt(10)
	v_mfma_f32_32x32x16_bf16 v[32:47], v[124:127], v[4:7], v[32:47]
	ds_read_b128 v[0:3], v191 offset:64
	ds_read_b128 v[4:7], v191 offset:96
	s_waitcnt lgkmcnt(1)
	v_mfma_f32_32x32x16_bf16 v[48:63], v[72:75], v[0:3], v[48:63]
	s_waitcnt vmcnt(9)
	v_mfma_f32_32x32x16_bf16 v[32:47], v[136:139], v[0:3], v[32:47]
	s_waitcnt lgkmcnt(0)
	v_mfma_f32_32x32x16_bf16 v[48:63], v[76:79], v[4:7], v[48:63]
	s_waitcnt vmcnt(8)
	v_mfma_f32_32x32x16_bf16 v[32:47], v[140:143], v[4:7], v[32:47]
	ds_read_b128 v[0:3], v191 offset:128
	ds_read_b128 v[4:7], v191 offset:160
	s_waitcnt lgkmcnt(1)
	v_mfma_f32_32x32x16_bf16 v[48:63], v[80:83], v[0:3], v[48:63]
	s_waitcnt vmcnt(7)
	v_mfma_f32_32x32x16_bf16 v[32:47], v[144:147], v[0:3], v[32:47]
	s_waitcnt lgkmcnt(0)
	v_mfma_f32_32x32x16_bf16 v[48:63], v[84:87], v[4:7], v[48:63]
	s_waitcnt vmcnt(6)
	v_mfma_f32_32x32x16_bf16 v[32:47], v[148:151], v[4:7], v[32:47]
	ds_read_b128 v[0:3], v191 offset:192
	ds_read_b128 v[4:7], v191 offset:224
	ds_read_b128 v[16:19], v191 offset:8704
	ds_read_b128 v[180:183], v191 offset:8736
	s_waitcnt lgkmcnt(3)
	v_mfma_f32_32x32x16_bf16 v[48:63], v[88:91], v[0:3], v[48:63]
	s_waitcnt vmcnt(5)
	v_mfma_f32_32x32x16_bf16 v[32:47], v[152:155], v[0:3], v[32:47]
	s_waitcnt lgkmcnt(2)
	v_mfma_f32_32x32x16_bf16 v[48:63], v[92:95], v[4:7], v[48:63]
	s_waitcnt vmcnt(4)
	v_mfma_f32_32x32x16_bf16 v[32:47], v[156:159], v[4:7], v[32:47]
	s_nop 9
	v_max_f32_e32 v20, 0, v48
	v_fma_f32 v193, v96, v20, 0
	v_max_f32_e32 v52, 0, v52
	s_waitcnt lgkmcnt(1)
	v_mfma_f32_32x32x16_bf16 v[0:15], v[64:67], v[16:19], 0
	v_max_f32_e32 v32, 0, v32
	s_waitcnt vmcnt(3)
	v_fma_f32 v196, v160, v32, 0
	v_max_f32_e32 v32, 0, v49
	v_fmac_f32_e32 v193, v97, v32
	v_max_f32_e32 v32, 0, v33
	v_mfma_f32_32x32x16_bf16 v[16:31], v[112:115], v[16:19], 0
	v_fmac_f32_e32 v196, v161, v32
	v_max_f32_e32 v32, 0, v50
	v_fmac_f32_e32 v193, v98, v32
	v_max_f32_e32 v32, 0, v34
	v_fmac_f32_e32 v196, v162, v32
	s_waitcnt lgkmcnt(0)
	v_mfma_f32_32x32x16_bf16 v[0:15], v[68:71], v[180:183], v[0:15]
	v_max_f32_e32 v32, v51, v51
	ds_read_b128 v[48:51], v191 offset:8768
	v_max_f32_e32 v32, 0, v32
	v_fmac_f32_e32 v193, v99, v32
	v_max_f32_e32 v36, 0, v36
	v_fmac_f32_e32 v193, v100, v52
	v_mfma_f32_32x32x16_bf16 v[16:31], v[124:127], v[180:183], v[16:31]
	v_max_f32_e32 v180, 0, v35
	ds_read_b128 v[32:35], v191 offset:8800
	v_fmac_f32_e32 v196, v163, v180
	s_waitcnt vmcnt(2)
	v_fmac_f32_e32 v196, v164, v36
	v_max_f32_e32 v36, 0, v53
	s_waitcnt lgkmcnt(1)
	v_mfma_f32_32x32x16_bf16 v[0:15], v[72:75], v[48:51], v[0:15]
	v_fmac_f32_e32 v193, v101, v36
	v_max_f32_e32 v36, 0, v37
	v_fmac_f32_e32 v196, v165, v36
	v_max_f32_e32 v36, 0, v54
	v_fmac_f32_e32 v193, v102, v36
	v_mfma_f32_32x32x16_bf16 v[16:31], v[136:139], v[48:51], v[16:31]
	v_max_f32_e32 v36, 0, v38
	v_fmac_f32_e32 v196, v166, v36
	v_max_f32_e32 v40, 0, v40
	s_waitcnt lgkmcnt(0)
	v_mfma_f32_32x32x16_bf16 v[0:15], v[76:79], v[32:35], v[0:15]
	v_max_f32_e32 v48, 0, v56
	v_mfma_f32_32x32x16_bf16 v[16:31], v[140:143], v[32:35], v[16:31]
	v_max_f32_e32 v32, 0, v55
	v_fmac_f32_e32 v193, v103, v32
	ds_read_b128 v[32:35], v191 offset:8832
	v_max_f32_e32 v36, 0, v39
	v_fmac_f32_e32 v196, v167, v36
	ds_read_b128 v[36:39], v191 offset:8864
	s_waitcnt lgkmcnt(1)
	v_mfma_f32_32x32x16_bf16 v[0:15], v[80:83], v[32:35], v[0:15]
	s_waitcnt vmcnt(1)
	v_fmac_f32_e32 v196, v168, v40
	v_fmac_f32_e32 v193, v104, v48
	ds_read_b128 v[48:51], v191 offset:17408
	v_mfma_f32_32x32x16_bf16 v[16:31], v[144:147], v[32:35], v[16:31]
	v_max_f32_e32 v32, 0, v57
	v_fmac_f32_e32 v193, v105, v32
	v_max_f32_e32 v32, 0, v41
	v_fmac_f32_e32 v196, v169, v32
	v_max_f32_e32 v32, 0, v58
	v_fmac_f32_e32 v193, v106, v32
	v_max_f32_e32 v32, 0, v42
	s_waitcnt lgkmcnt(1)
	v_mfma_f32_32x32x16_bf16 v[0:15], v[84:87], v[36:39], v[0:15]
	v_fmac_f32_e32 v196, v170, v32
	v_max_f32_e32 v32, 0, v59
	v_fmac_f32_e32 v193, v107, v32
	v_mfma_f32_32x32x16_bf16 v[16:31], v[148:151], v[36:39], v[16:31]
	v_max_f32_e32 v36, 0, v43
	ds_read_b128 v[32:35], v191 offset:8896
	v_fmac_f32_e32 v196, v171, v36
	v_max_f32_e32 v40, 0, v60
	ds_read_b128 v[36:39], v191 offset:8928
	v_fmac_f32_e32 v193, v108, v40
	s_waitcnt lgkmcnt(1)
	v_mfma_f32_32x32x16_bf16 v[0:15], v[88:91], v[32:35], v[0:15]
	v_max_f32_e32 v40, 0, v44
	s_waitcnt vmcnt(0)
	v_fmac_f32_e32 v196, v172, v40
	v_max_f32_e32 v40, 0, v61
	v_fmac_f32_e32 v193, v109, v40
	v_mfma_f32_32x32x16_bf16 v[16:31], v[152:155], v[32:35], v[16:31]
	v_max_f32_e32 v32, 0, v45
	v_fmac_f32_e32 v196, v173, v32
	v_max_f32_e32 v32, 0, v62
	v_fmac_f32_e32 v193, v110, v32
	s_waitcnt lgkmcnt(0)
; #define LAS __attribute__((address_space(3)))
; #define IDX_WRITEK(buf) do { LAS unsigned char* d = lds + (buf) * (TK * PITCH) + srow * PITCH + sseg * 64; *(LAS u32x4*)d = st0; *(LAS u32x4*)(d + 16) = st1; *(LAS u32x4*)(d + 32) = st2; *(LAS u32x4*)(d + 48) = st3; } while (0)
; __device__ __forceinline__ void idx_stream(unsigned char* ws, LAS unsigned char* lds, int bb, int bid, int G, int wave, int lane, int tid) {
;     ...
;         for (int ct = 0; ct < TK / 32; ++ct) {
;             bf16x8 bfr[8];
; #pragma unroll
;             for (int ks = 0; ks < 8; ++ks) bfr[ks] = *(const LAS bf16x8*)(kb + ct * 32 * PITCH + ks * 32);
;             f32x16 c0, c1;
; #pragma unroll
;             for (int r = 0; r < 16; ++r) { c0[r] = 0.f; c1[r] = 0.f; }
; #pragma unroll
;             for (int ks = 0; ks < 8; ++ks) { c0 = __builtin_amdgcn_mfma_f32_32x32x16_bf16(af[0][ks], bfr[ks], c0, 0, 0, 0); c1 = __builtin_amdgcn_mfma_f32_32x32x16_bf16(af[1][ks], bfr[ks], c1, 0, 0, 0); }
;             float s0 = 0.f, s1 = 0.f;
; #pragma unroll
;             for (int r = 0; r < 16; ++r) { s0 += w[0][r] * fmaxf(c0[r], 0.f); s1 += w[1][r] * fmaxf(c1[r], 0.f); }
;             const int key = kt * TK + ct * 32 + rho, q = 32 * u + 4 * wave + hi;
;             SC[(size_t)q * SEQ + key] = (_Float16)s0; SC[(size_t)(q + 2) * SEQ + key] = (_Float16)s1;
;         }
;         if (g + 1 < g1) IDX_WRITEK(buf ^ 1);
	v_mfma_f32_32x32x16_bf16 v[0:15], v[92:95], v[36:39], v[0:15]
	v_max_f32_e32 v32, 0, v46
	v_fmac_f32_e32 v196, v174, v32
	v_max_f32_e32 v32, 0, v63
	v_fma_mixlo_f16 v32, v111, v32, v193
	v_ashrrev_i32_e32 v193, 31, v192
	v_mfma_f32_32x32x16_bf16 v[16:31], v[156:159], v[36:39], v[16:31]
	v_lshl_add_u64 v[180:181], v[192:193], 1, v[194:195]
	v_max_f32_e32 v33, 0, v47
	v_add_co_u32_e32 v52, vcc, s9, v180
	s_nop 0
	global_store_short v[180:181], v32, off
	v_fma_mixlo_f16 v54, v175, v33, v196
	ds_read_b128 v[192:195], v191 offset:17440
	v_mfma_f32_32x32x16_bf16 v[32:47], v[64:67], v[48:51], 0
	v_addc_co_u32_e32 v53, vcc, 0, v181, vcc
	v_max_f32_e32 v0, 0, v0
	global_store_short v[52:53], v54, off
	v_fma_f32 v196, v96, v0, 0
	v_max_f32_e32 v0, 0, v16
	v_mfma_f32_32x32x16_bf16 v[48:63], v[112:115], v[48:51], 0
	v_fma_f32 v197, v160, v0, 0
	v_max_f32_e32 v0, 0, v1
	v_fmac_f32_e32 v196, v97, v0
	v_max_f32_e32 v0, 0, v17
	v_fmac_f32_e32 v197, v161, v0
	s_waitcnt lgkmcnt(0)
	v_mfma_f32_32x32x16_bf16 v[32:47], v[68:71], v[192:195], v[32:47]
	v_max_f32_e32 v0, 0, v2
	v_fmac_f32_e32 v196, v98, v0
	v_max_f32_e32 v0, 0, v18
	v_fmac_f32_e32 v197, v162, v0
	v_max_f32_e32 v16, v3, v3
	ds_read_b128 v[0:3], v191 offset:17472
	v_mfma_f32_32x32x16_bf16 v[48:63], v[124:127], v[192:195], v[48:63]
	v_max_f32_e32 v16, 0, v16
	v_fmac_f32_e32 v196, v99, v16
	v_max_f32_e32 v192, v19, v19
	ds_read_b128 v[16:19], v191 offset:17504
	v_max_f32_e32 v4, 0, v4
	v_max_f32_e32 v192, 0, v192
	s_waitcnt lgkmcnt(1)
	v_mfma_f32_32x32x16_bf16 v[32:47], v[72:75], v[0:3], v[32:47]
	v_fmac_f32_e32 v196, v100, v4
	v_fmac_f32_e32 v197, v163, v192
	v_max_f32_e32 v4, 0, v20
	v_fmac_f32_e32 v197, v164, v4
	v_mfma_f32_32x32x16_bf16 v[48:63], v[136:139], v[0:3], v[48:63]
	v_max_f32_e32 v0, 0, v5
	v_fmac_f32_e32 v196, v101, v0
	v_max_f32_e32 v0, 0, v21
	v_fmac_f32_e32 v197, v165, v0
	v_max_f32_e32 v0, 0, v6
	v_fmac_f32_e32 v196, v102, v0
	s_waitcnt lgkmcnt(0)
	v_mfma_f32_32x32x16_bf16 v[32:47], v[76:79], v[16:19], v[32:47]
	v_max_f32_e32 v0, 0, v22
	v_fmac_f32_e32 v197, v166, v0
	v_max_f32_e32 v0, 0, v7
	v_fmac_f32_e32 v196, v103, v0
	ds_read_b128 v[0:3], v191 offset:17536
	v_max_f32_e32 v8, 0, v8
	v_mfma_f32_32x32x16_bf16 v[48:63], v[140:143], v[16:19], v[48:63]
	v_max_f32_e32 v4, 0, v23
	v_fmac_f32_e32 v196, v104, v8
	v_fmac_f32_e32 v197, v167, v4
	v_max_f32_e32 v8, 0, v24
	ds_read_b128 v[4:7], v191 offset:17568
	v_fmac_f32_e32 v197, v168, v8
	s_waitcnt lgkmcnt(1)
	v_mfma_f32_32x32x16_bf16 v[32:47], v[80:83], v[0:3], v[32:47]
	v_lshl_add_u64 v[182:183], v[180:181], 0, s[14:15]
	ds_read_b128 v[16:19], v191 offset:26112
	ds_read_b128 v[192:195], v191 offset:26144
	s_andn2_b64 vcc, exec, s[20:21]
	v_mfma_f32_32x32x16_bf16 v[48:63], v[144:147], v[0:3], v[48:63]
	v_max_f32_e32 v0, 0, v9
	v_fmac_f32_e32 v196, v105, v0
	v_max_f32_e32 v0, 0, v25
	v_fmac_f32_e32 v197, v169, v0
	v_max_f32_e32 v0, 0, v10
	v_fmac_f32_e32 v196, v106, v0
	v_max_f32_e32 v0, 0, v26
	s_waitcnt lgkmcnt(2)
	v_mfma_f32_32x32x16_bf16 v[32:47], v[84:87], v[4:7], v[32:47]
	v_fmac_f32_e32 v197, v170, v0
	v_max_f32_e32 v0, 0, v11
	v_fmac_f32_e32 v196, v107, v0
	v_mfma_f32_32x32x16_bf16 v[48:63], v[148:151], v[4:7], v[48:63]
	v_max_f32_e32 v4, 0, v27
	ds_read_b128 v[0:3], v191 offset:17600
	v_fmac_f32_e32 v197, v171, v4
	v_max_f32_e32 v8, 0, v12
	ds_read_b128 v[4:7], v191 offset:17632
	v_fmac_f32_e32 v196, v108, v8
	s_waitcnt lgkmcnt(1)
	v_mfma_f32_32x32x16_bf16 v[32:47], v[88:91], v[0:3], v[32:47]
	v_max_f32_e32 v8, 0, v28
	v_fmac_f32_e32 v197, v172, v8
	v_max_f32_e32 v8, 0, v13
	v_fmac_f32_e32 v196, v109, v8
	v_mfma_f32_32x32x16_bf16 v[48:63], v[152:155], v[0:3], v[48:63]
	v_max_f32_e32 v0, 0, v29
	v_fmac_f32_e32 v197, v173, v0
	v_max_f32_e32 v0, 0, v14
	v_fmac_f32_e32 v196, v110, v0
	s_waitcnt lgkmcnt(0)
	v_mfma_f32_32x32x16_bf16 v[32:47], v[92:95], v[4:7], v[32:47]
	v_max_f32_e32 v0, 0, v30
	v_fmac_f32_e32 v197, v174, v0
	v_max_f32_e32 v0, 0, v15
	v_max_f32_e32 v1, 0, v31
	v_fma_mixlo_f16 v0, v111, v0, v196
	v_mfma_f32_32x32x16_bf16 v[48:63], v[156:159], v[4:7], v[48:63]
	global_store_short v[180:181], v0, off offset:64
	v_fma_mixlo_f16 v0, v175, v1, v197
	global_store_short v[182:183], v0, off offset:64
	s_nop 0
	s_nop 1
	v_max_f32_e32 v0, v32, v32
	v_max_f32_e32 v20, 0, v0
	v_fma_f32 v196, v96, v20, 0
	s_nop 3
	v_max_f32_e32 v20, 0, v48
	v_fma_f32 v197, v160, v20, 0
	v_mfma_f32_32x32x16_bf16 v[0:15], v[64:67], v[16:19], 0
	v_max_f32_e32 v20, 0, v33
	v_fmac_f32_e32 v196, v97, v20
	v_max_f32_e32 v32, 0, v49
	v_fmac_f32_e32 v197, v161, v32
	v_max_f32_e32 v32, 0, v34
	v_mfma_f32_32x32x16_bf16 v[16:31], v[112:115], v[16:19], 0
	v_fmac_f32_e32 v196, v98, v32
	v_max_f32_e32 v32, 0, v50
	v_fmac_f32_e32 v197, v162, v32
	v_max_f32_e32 v32, 0, v35
	v_fmac_f32_e32 v196, v99, v32
	v_mfma_f32_32x32x16_bf16 v[0:15], v[68:71], v[192:195], v[0:15]
	v_max_f32_e32 v32, 0, v51
	v_fmac_f32_e32 v197, v163, v32
	ds_read_b128 v[32:35], v191 offset:26176
	ds_read_b128 v[48:51], v191 offset:26208
	v_max_f32_e32 v36, 0, v36
	v_fmac_f32_e32 v196, v100, v36
	v_mfma_f32_32x32x16_bf16 v[16:31], v[124:127], v[192:195], v[16:31]
	v_max_f32_e32 v36, 0, v52
	v_fmac_f32_e32 v197, v164, v36
	v_max_f32_e32 v36, 0, v37
	v_fmac_f32_e32 v196, v101, v36
	s_waitcnt lgkmcnt(1)
; #define LAS __attribute__((address_space(3)))
; #define IDX_WRITEK(buf) do { LAS unsigned char* d = lds + (buf) * (TK * PITCH) + srow * PITCH + sseg * 64; *(LAS u32x4*)d = st0; *(LAS u32x4*)(d + 16) = st1; *(LAS u32x4*)(d + 32) = st2; *(LAS u32x4*)(d + 48) = st3; } while (0)
; __device__ __forceinline__ void idx_stream(unsigned char* ws, LAS unsigned char* lds, int bb, int bid, int G, int wave, int lane, int tid) {
;     ...
;         for (int ct = 0; ct < TK / 32; ++ct) {
;             bf16x8 bfr[8];
; #pragma unroll
;             for (int ks = 0; ks < 8; ++ks) bfr[ks] = *(const LAS bf16x8*)(kb + ct * 32 * PITCH + ks * 32);
;             f32x16 c0, c1;
; #pragma unroll
;             for (int r = 0; r < 16; ++r) { c0[r] = 0.f; c1[r] = 0.f; }
; #pragma unroll
;             for (int ks = 0; ks < 8; ++ks) { c0 = __builtin_amdgcn_mfma_f32_32x32x16_bf16(af[0][ks], bfr[ks], c0, 0, 0, 0); c1 = __builtin_amdgcn_mfma_f32_32x32x16_bf16(af[1][ks], bfr[ks], c1, 0, 0, 0); }
;             float s0 = 0.f, s1 = 0.f;
; #pragma unroll
;             for (int r = 0; r < 16; ++r) { s0 += w[0][r] * fmaxf(c0[r], 0.f); s1 += w[1][r] * fmaxf(c1[r], 0.f); }
;             const int key = kt * TK + ct * 32 + rho, q = 32 * u + 4 * wave + hi;
;             SC[(size_t)q * SEQ + key] = (_Float16)s0; SC[(size_t)(q + 2) * SEQ + key] = (_Float16)s1;
;         }
;         if (g + 1 < g1) IDX_WRITEK(buf ^ 1);
	v_mfma_f32_32x32x16_bf16 v[0:15], v[72:75], v[32:35], v[0:15]
	v_max_f32_e32 v36, 0, v53
	v_fmac_f32_e32 v197, v165, v36
	v_max_f32_e32 v36, 0, v56
	v_mfma_f32_32x32x16_bf16 v[16:31], v[136:139], v[32:35], v[16:31]
	v_max_f32_e32 v32, 0, v38
	v_fmac_f32_e32 v196, v102, v32
	v_max_f32_e32 v32, 0, v54
	v_fmac_f32_e32 v197, v166, v32
	v_max_f32_e32 v32, 0, v39
	v_fmac_f32_e32 v196, v103, v32
	s_waitcnt lgkmcnt(0)
	v_mfma_f32_32x32x16_bf16 v[0:15], v[76:79], v[48:51], v[0:15]
	v_max_f32_e32 v32, 0, v55
	v_fmac_f32_e32 v197, v167, v32
	v_max_f32_e32 v32, 0, v40
	v_fmac_f32_e32 v196, v104, v32
	ds_read_b128 v[32:35], v191 offset:26240
	v_mfma_f32_32x32x16_bf16 v[16:31], v[140:143], v[48:51], v[16:31]
	v_max_f32_e32 v40, 0, v41
	v_fmac_f32_e32 v196, v105, v40
	v_fmac_f32_e32 v197, v168, v36
	v_max_f32_e32 v40, 0, v57
	ds_read_b128 v[36:39], v191 offset:26272
	v_fmac_f32_e32 v197, v169, v40
	s_waitcnt lgkmcnt(1)
	v_mfma_f32_32x32x16_bf16 v[0:15], v[80:83], v[32:35], v[0:15]
	v_mfma_f32_32x32x16_bf16 v[16:31], v[144:147], v[32:35], v[16:31]
	v_max_f32_e32 v32, 0, v42
	v_fmac_f32_e32 v196, v106, v32
	v_max_f32_e32 v32, 0, v58
	v_fmac_f32_e32 v197, v170, v32
	v_max_f32_e32 v32, 0, v43
	v_fmac_f32_e32 v196, v107, v32
	v_max_f32_e32 v32, 0, v59
	s_waitcnt lgkmcnt(0)
	v_mfma_f32_32x32x16_bf16 v[0:15], v[84:87], v[36:39], v[0:15]
	v_fmac_f32_e32 v197, v171, v32
	v_max_f32_e32 v32, 0, v44
	v_fmac_f32_e32 v196, v108, v32
	v_mfma_f32_32x32x16_bf16 v[16:31], v[148:151], v[36:39], v[16:31]
	v_max_f32_e32 v36, 0, v60
	ds_read_b128 v[32:35], v191 offset:26304
	v_fmac_f32_e32 v197, v172, v36
	v_max_f32_e32 v40, 0, v45
	ds_read_b128 v[36:39], v191 offset:26336
	v_fmac_f32_e32 v196, v109, v40
	s_waitcnt lgkmcnt(1)
	v_mfma_f32_32x32x16_bf16 v[0:15], v[88:91], v[32:35], v[0:15]
	v_max_f32_e32 v40, 0, v61
	v_fmac_f32_e32 v197, v173, v40
	v_max_f32_e32 v40, 0, v46
	v_fmac_f32_e32 v196, v110, v40
	v_mfma_f32_32x32x16_bf16 v[16:31], v[152:155], v[32:35], v[16:31]
	v_max_f32_e32 v32, 0, v62
	v_fmac_f32_e32 v197, v174, v32
	v_max_f32_e32 v32, 0, v47
	v_max_f32_e32 v33, 0, v63
	s_waitcnt lgkmcnt(0)
	v_mfma_f32_32x32x16_bf16 v[0:15], v[92:95], v[36:39], v[0:15]
	v_fma_mixlo_f16 v32, v111, v32, v196
	global_store_short v[180:181], v32, off offset:128
	v_fma_mixlo_f16 v32, v175, v33, v197
	global_store_short v[182:183], v32, off offset:128
	v_mfma_f32_32x32x16_bf16 v[16:31], v[156:159], v[36:39], v[16:31]
	s_nop 6
	v_max_f32_e32 v0, 0, v0
	v_fma_f32 v0, v96, v0, 0
	v_max_f32_e32 v1, 0, v1
	v_fmac_f32_e32 v0, v97, v1
	s_nop 0
	v_max_f32_e32 v16, 0, v16
	v_fma_f32 v16, v160, v16, 0
	v_max_f32_e32 v1, 0, v17
	v_fmac_f32_e32 v16, v161, v1
	v_max_f32_e32 v1, 0, v2
	v_fmac_f32_e32 v0, v98, v1
	v_max_f32_e32 v1, 0, v18
	v_fmac_f32_e32 v16, v162, v1
	v_max_f32_e32 v1, 0, v3
	v_fmac_f32_e32 v0, v99, v1
	v_max_f32_e32 v1, 0, v19
	v_fmac_f32_e32 v16, v163, v1
	v_max_f32_e32 v1, 0, v4
	v_fmac_f32_e32 v0, v100, v1
	v_max_f32_e32 v1, 0, v20
	v_fmac_f32_e32 v16, v164, v1
	v_max_f32_e32 v1, 0, v5
	v_fmac_f32_e32 v0, v101, v1
	v_max_f32_e32 v1, 0, v21
	v_fmac_f32_e32 v16, v165, v1
	v_max_f32_e32 v1, 0, v6
	v_fmac_f32_e32 v0, v102, v1
	v_max_f32_e32 v1, 0, v22
	v_fmac_f32_e32 v16, v166, v1
	v_max_f32_e32 v1, 0, v7
	v_fmac_f32_e32 v0, v103, v1
	v_max_f32_e32 v1, 0, v23
	v_fmac_f32_e32 v16, v167, v1
	v_max_f32_e32 v1, 0, v8
	v_fmac_f32_e32 v0, v104, v1
	v_max_f32_e32 v1, 0, v24
	v_fmac_f32_e32 v16, v168, v1
	v_max_f32_e32 v1, 0, v9
	v_fmac_f32_e32 v0, v105, v1
	v_max_f32_e32 v1, 0, v25
	v_fmac_f32_e32 v16, v169, v1
	v_max_f32_e32 v1, 0, v10
	v_fmac_f32_e32 v0, v106, v1
	v_max_f32_e32 v1, 0, v26
	v_fmac_f32_e32 v16, v170, v1
	v_max_f32_e32 v1, 0, v11
	v_fmac_f32_e32 v0, v107, v1
	v_max_f32_e32 v1, 0, v27
	v_fmac_f32_e32 v16, v171, v1
	v_max_f32_e32 v1, 0, v12
	v_fmac_f32_e32 v0, v108, v1
	v_max_f32_e32 v1, 0, v28
	v_fmac_f32_e32 v16, v172, v1
	v_max_f32_e32 v1, 0, v13
	v_fmac_f32_e32 v0, v109, v1
	v_max_f32_e32 v1, 0, v29
	v_fmac_f32_e32 v16, v173, v1
	v_max_f32_e32 v1, 0, v14
	v_fmac_f32_e32 v0, v110, v1
	v_max_f32_e32 v1, 0, v30
	v_fmac_f32_e32 v16, v174, v1
	v_max_f32_e32 v1, 0, v15
	v_max_f32_e32 v2, 0, v31
	v_fma_mixlo_f16 v0, v111, v1, v0
	global_store_short v[180:181], v0, off offset:192
	v_fma_mixlo_f16 v0, v175, v2, v16
	global_store_short v[182:183], v0, off offset:192
	s_cbranch_vccnz .LBB0_1151
	s_xor_b32 s20, s23, 1
	s_mul_i32 s20, s20, 0x8800
	v_add_u32_e32 v0, s20, v186
	s_waitcnt vmcnt(8)
	ds_write_b128 v0, v[128:131]
	ds_write_b128 v0, v[116:119] offset:16
	ds_write_b128 v0, v[132:135] offset:32
	ds_write_b128 v0, v[120:123] offset:48
